# EpiResid (down/out/o): first 4 residual loads of the second row half prefetched with the first half
# speedup vs baseline: 1.0329x; 1.0007x over previous
.LBB7_437:
	s_waitcnt lgkmcnt(0)
	v_lshl_or_b32 v2, s10, 8, v206
	v_lshl_add_u32 v184, s89, 8, v204
	v_ashrrev_i32_e32 v3, 31, v2
	v_lshlrev_b64 v[132:133], 1, v[2:3]
	v_ashrrev_i32_e32 v185, 31, v184
	v_lshl_add_u64 v[190:191], s[68:69], 0, v[132:133]
	v_lshlrev_b64 v[134:135], 11, v[184:185]
	v_lshl_add_u64 v[136:137], v[190:191], 0, v[134:135]
	global_load_dwordx4 v[196:199], v[136:137], off
	global_load_dwordx4 v[208:211], v[136:137], off offset:256
	v_or_b32_e32 v192, 16, v184
	v_or_b32_e32 v186, 32, v184
	v_or_b32_e32 v156, 48, v184
	v_ashrrev_i32_e32 v193, 31, v192
	v_ashrrev_i32_e32 v187, 31, v186
	v_ashrrev_i32_e32 v157, 31, v156
	v_lshlrev_b64 v[194:195], 11, v[192:193]
	v_lshlrev_b64 v[188:189], 11, v[186:187]
	v_lshlrev_b64 v[158:159], 11, v[156:157]
	v_lshl_add_u64 v[134:135], s[68:69], 0, v[134:135]
	v_lshl_add_u64 v[136:137], v[190:191], 0, v[194:195]
	v_lshl_add_u64 v[138:139], v[190:191], 0, v[188:189]
	v_lshl_add_u64 v[170:171], v[190:191], 0, v[158:159]
	v_lshl_add_u64 v[172:173], v[134:135], 0, v[132:133]
	global_load_dwordx4 v[152:155], v[136:137], off
	global_load_dwordx4 v[148:151], v[136:137], off offset:256
	global_load_dwordx4 v[144:147], v[138:139], off
	global_load_dwordx4 v[140:143], v[138:139], off offset:256
	s_nop 0
	global_load_dwordx4 v[136:139], v[170:171], off
	global_load_dwordx4 v[132:135], v[170:171], off offset:256
	v_add_u32_e32 v248, 0x80, v184
	v_ashrrev_i32_e32 v249, 31, v248
	v_lshlrev_b64 v[248:249], 11, v[248:249]
	v_lshl_add_u64 v[248:249], v[190:191], 0, v[248:249]
	global_load_dwordx4 v[232:235], v[248:249], off
	global_load_dwordx4 v[236:239], v[248:249], off offset:256
	s_mov_b64 s[72:73], 0x8000
	v_lshl_add_u64 v[248:249], v[248:249], 0, s[72:73]
	global_load_dwordx4 v[240:243], v[248:249], off
	global_load_dwordx4 v[244:247], v[248:249], off offset:256
	s_lshl_b32 s16, s10, 2
	s_ashr_i32 s17, s16, 31
	s_waitcnt vmcnt(0)
	v_lshlrev_b32_e32 v212, 16, v198
	v_and_b32_e32 v213, 0xffff0000, v198
	v_lshlrev_b32_e32 v198, 16, v199
	v_and_b32_e32 v199, 0xffff0000, v199
	v_lshlrev_b32_e32 v170, 16, v196
	v_and_b32_e32 v171, 0xffff0000, v196
	v_lshlrev_b32_e32 v196, 16, v197
	v_and_b32_e32 v197, 0xffff0000, v197
	v_pk_fma_f32 v[220:221], v[126:127], 0.5, v[198:199] op_sel_hi:[1,0,1]
	v_pk_fma_f32 v[198:199], v[124:125], 0.5, v[212:213] op_sel_hi:[1,0,1]
	v_lshlrev_b32_e32 v214, 16, v208
	v_and_b32_e32 v215, 0xffff0000, v208
	v_lshlrev_b32_e32 v208, 16, v209
	v_and_b32_e32 v209, 0xffff0000, v209
	v_lshlrev_b32_e32 v216, 16, v210
	v_and_b32_e32 v217, 0xffff0000, v210
	v_lshlrev_b32_e32 v210, 16, v211
	v_and_b32_e32 v211, 0xffff0000, v211
	v_pk_fma_f32 v[218:219], v[130:131], 0.5, v[196:197] op_sel_hi:[1,0,1]
	v_pk_fma_f32 v[170:171], v[128:129], 0.5, v[170:171] op_sel_hi:[1,0,1]
	v_pk_fma_f32 v[208:209], v[98:99], 0.5, v[208:209] op_sel_hi:[1,0,1]
	v_cvt_pk_bf16_f32 v196, v170, v171
	v_cvt_pk_bf16_f32 v197, v218, v219
	v_cvt_pk_bf16_f32 v198, v198, v199
	v_cvt_pk_bf16_f32 v199, v220, v221
	v_pk_fma_f32 v[212:213], v[96:97], 0.5, v[214:215] op_sel_hi:[1,0,1]
	v_pk_fma_f32 v[214:215], v[94:95], 0.5, v[210:211] op_sel_hi:[1,0,1]
	global_store_dwordx4 v[172:173], v[196:199], off
	v_lshlrev_b32_e32 v0, 16, v196
	v_and_b32_e32 v170, 0xffff0000, v196
	v_lshlrev_b32_e32 v171, 16, v197
	v_and_b32_e32 v196, 0xffff0000, v197
	v_lshlrev_b32_e32 v197, 16, v198
	v_and_b32_e32 v198, 0xffff0000, v198
	v_lshlrev_b32_e32 v218, 16, v199
	v_and_b32_e32 v199, 0xffff0000, v199
	v_pk_fma_f32 v[216:217], v[92:93], 0.5, v[216:217] op_sel_hi:[1,0,1]
	v_cvt_pk_bf16_f32 v210, v212, v213
	v_cvt_pk_bf16_f32 v211, v208, v209
	v_mul_f32_e32 v170, v170, v170
	v_cvt_pk_bf16_f32 v212, v216, v217
	v_cvt_pk_bf16_f32 v213, v214, v215
	v_mul_f32_e32 v196, v196, v196
	v_mul_f32_e32 v198, v198, v198
	v_mul_f32_e32 v199, v199, v199
	v_and_b32_e32 v209, 0xffff0000, v210
	v_and_b32_e32 v215, 0xffff0000, v211
	v_lshlrev_b32_e32 v208, 16, v210
	v_lshlrev_b32_e32 v214, 16, v211
	v_fmac_f32_e32 v170, v0, v0
	v_fmac_f32_e32 v196, v171, v171
	v_fmac_f32_e32 v198, v197, v197
	v_fmac_f32_e32 v199, v218, v218
	v_mul_f32_e32 v0, v209, v209
	v_mul_f32_e32 v171, v215, v215
	v_and_b32_e32 v217, 0xffff0000, v212
	v_and_b32_e32 v220, 0xffff0000, v213
	v_add_f32_e32 v170, v170, v196
	v_add_f32_e32 v196, v198, v199
	v_fmac_f32_e32 v0, v208, v208
	v_fmac_f32_e32 v171, v214, v214
	v_lshlrev_b32_e32 v216, 16, v212
	v_lshlrev_b32_e32 v219, 16, v213
	v_add_f32_e32 v170, v170, v196
	v_add_f32_e32 v0, v0, v171
	v_mul_f32_e32 v171, v217, v217
	v_mul_f32_e32 v196, v220, v220
	v_fmac_f32_e32 v171, v216, v216
	v_fmac_f32_e32 v196, v219, v219
	v_add_f32_e32 v171, v171, v196
	v_add_f32_e32 v0, v0, v171
	v_and_b32_e32 v171, 64, v163
	v_add_f32_e32 v170, v170, v0
	v_xor_b32_e32 v0, 16, v163
	v_add_u32_e32 v171, 64, v171
	v_cmp_lt_i32_e32 vcc, v0, v171
	global_store_dwordx4 v[172:173], v[210:213], off offset:256
	s_nop 0
	v_cndmask_b32_e32 v0, v163, v0, vcc
	v_lshlrev_b32_e32 v0, 2, v0
	ds_bpermute_b32 v196, v0, v170
	s_waitcnt lgkmcnt(0)
	v_add_f32_e32 v196, v170, v196
	v_xor_b32_e32 v170, 32, v163
	v_cmp_lt_i32_e32 vcc, v170, v171
	s_nop 1
	v_cndmask_b32_e32 v170, v163, v170, vcc
	v_lshlrev_b32_e32 v208, 2, v170
	ds_bpermute_b32 v197, v208, v196
	s_and_saveexec_b64 s[72:73], s[40:41]
	s_cbranch_execz .LBB7_439
	v_lshlrev_b64 v[170:171], 6, v[184:185]
	v_lshl_add_u64 v[170:171], s[66:67], 0, v[170:171]
	v_lshl_add_u64 v[170:171], s[16:17], 2, v[170:171]
	s_lshl_b32 s20, s96, 2
	v_lshl_add_u64 v[170:171], v[170:171], 0, s[20:21]
	s_waitcnt lgkmcnt(0)
	v_add_f32_e32 v172, v196, v197
	global_store_dword v[170:171], v172, off

.LBB7_445:
	s_or_b64 exec, exec, s[72:73]
	v_add_u32_e32 v198, 0x80, v184
	v_ashrrev_i32_e32 v199, 31, v198
	v_lshlrev_b64 v[170:171], 11, v[198:199]
	s_waitcnt lgkmcnt(0)
	v_lshl_add_u64 v[132:133], v[190:191], 0, v[170:171]
	v_mov_b64_e32 v[210:211], v[232:233]
	v_mov_b64_e32 v[212:213], v[234:235]
	v_mov_b64_e32 v[156:157], v[236:237]
	v_mov_b64_e32 v[158:159], v[238:239]
	v_add_u32_e32 v194, 0x90, v184
	v_ashrrev_i32_e32 v195, 31, v194
	v_add_u32_e32 v188, 0xa0, v184
	v_lshlrev_b64 v[196:197], 11, v[194:195]
	v_ashrrev_i32_e32 v189, 31, v188
	v_add_u32_e32 v184, 0xb0, v184
	v_lshl_add_u64 v[132:133], v[190:191], 0, v[196:197]
	v_lshlrev_b64 v[192:193], 11, v[188:189]
	v_ashrrev_i32_e32 v185, 31, v184
	v_mov_b64_e32 v[152:153], v[240:241]
	v_mov_b64_e32 v[154:155], v[242:243]
	v_mov_b64_e32 v[148:149], v[244:245]
	v_mov_b64_e32 v[150:151], v[246:247]
	v_lshl_add_u64 v[132:133], v[190:191], 0, v[192:193]
	v_lshlrev_b64 v[186:187], 11, v[184:185]
	global_load_dwordx4 v[144:147], v[132:133], off
	global_load_dwordx4 v[140:143], v[132:133], off offset:256
	v_lshl_add_u64 v[132:133], v[190:191], 0, v[186:187]
	global_load_dwordx4 v[136:139], v[132:133], off
	s_nop 0
	global_load_dwordx4 v[132:135], v[132:133], off offset:256
	v_lshl_add_u64 v[170:171], s[68:69], 0, v[170:171]
	v_lshl_add_u64 v[170:171], v[2:3], 1, v[170:171]
	s_waitcnt vmcnt(7)
	v_lshlrev_b32_e32 v172, 16, v210
	v_and_b32_e32 v173, 0xffff0000, v210
	v_lshlrev_b32_e32 v190, 16, v211
	v_and_b32_e32 v191, 0xffff0000, v211
	v_lshlrev_b32_e32 v210, 16, v212
	v_and_b32_e32 v211, 0xffff0000, v212
	v_lshlrev_b32_e32 v212, 16, v213
	v_and_b32_e32 v213, 0xffff0000, v213
	v_pk_fma_f32 v[172:173], v[68:69], 0.5, v[172:173] op_sel_hi:[1,0,1]
	v_pk_fma_f32 v[190:191], v[70:71], 0.5, v[190:191] op_sel_hi:[1,0,1]
	v_pk_fma_f32 v[214:215], v[62:63], 0.5, v[212:213] op_sel_hi:[1,0,1]
	v_pk_fma_f32 v[212:213], v[60:61], 0.5, v[210:211] op_sel_hi:[1,0,1]
	v_cvt_pk_bf16_f32 v210, v172, v173
	v_cvt_pk_bf16_f32 v211, v190, v191
	s_nop 0
	v_and_b32_e32 v173, 0xffff0000, v210
	v_lshlrev_b32_e32 v172, 16, v210
	v_and_b32_e32 v191, 0xffff0000, v211
	v_mul_f32_e32 v173, v173, v173
	v_cvt_pk_bf16_f32 v212, v212, v213
	v_lshlrev_b32_e32 v190, 16, v211
	v_fmac_f32_e32 v173, v172, v172
	v_mul_f32_e32 v172, v191, v191
	v_cvt_pk_bf16_f32 v213, v214, v215
	global_store_dwordx4 v[170:171], v[210:213], off
	v_lshlrev_b32_e32 v209, 16, v212
	v_fmac_f32_e32 v172, v190, v190
	v_and_b32_e32 v210, 0xffff0000, v212
	v_and_b32_e32 v212, 0xffff0000, v213
	v_lshlrev_b32_e32 v211, 16, v213
	v_add_f32_e32 v172, v173, v172
	v_mul_f32_e32 v173, v210, v210
	v_mul_f32_e32 v190, v212, v212
	v_fmac_f32_e32 v173, v209, v209
	v_fmac_f32_e32 v190, v211, v211
	v_add_f32_e32 v173, v173, v190
	v_add_f32_e32 v209, v172, v173
	s_waitcnt vmcnt(7)
	v_lshlrev_b32_e32 v172, 16, v156
	v_and_b32_e32 v173, 0xffff0000, v156
	v_lshlrev_b32_e32 v156, 16, v157
	v_and_b32_e32 v157, 0xffff0000, v157
	v_lshlrev_b32_e32 v190, 16, v158
	v_and_b32_e32 v191, 0xffff0000, v158
	v_lshlrev_b32_e32 v158, 16, v159
	v_and_b32_e32 v159, 0xffff0000, v159
	v_pk_fma_f32 v[210:211], v[34:35], 0.5, v[156:157] op_sel_hi:[1,0,1]
	v_pk_fma_f32 v[156:157], v[32:33], 0.5, v[172:173] op_sel_hi:[1,0,1]
	v_pk_fma_f32 v[172:173], v[30:31], 0.5, v[158:159] op_sel_hi:[1,0,1]
	v_pk_fma_f32 v[158:159], v[28:29], 0.5, v[190:191] op_sel_hi:[1,0,1]
	v_cvt_pk_bf16_f32 v156, v156, v157
	v_cvt_pk_bf16_f32 v157, v210, v211
	s_nop 0
	v_cvt_pk_bf16_f32 v158, v158, v159
	v_cvt_pk_bf16_f32 v159, v172, v173
	global_store_dwordx4 v[170:171], v[156:159], off offset:256
	v_lshlrev_b32_e32 v170, 16, v156
	v_lshlrev_b32_e32 v171, 16, v157
	v_and_b32_e32 v156, 0xffff0000, v156
	v_and_b32_e32 v157, 0xffff0000, v157
	v_mul_f32_e32 v156, v156, v156
	v_mul_f32_e32 v157, v157, v157
	v_lshlrev_b32_e32 v172, 16, v158
	v_and_b32_e32 v158, 0xffff0000, v158
	v_lshlrev_b32_e32 v173, 16, v159
	v_and_b32_e32 v159, 0xffff0000, v159
	v_fmac_f32_e32 v156, v170, v170
	v_fmac_f32_e32 v157, v171, v171
	v_add_f32_e32 v156, v156, v157
	v_mul_f32_e32 v157, v158, v158
	v_mul_f32_e32 v158, v159, v159
	v_fmac_f32_e32 v157, v172, v172
	v_fmac_f32_e32 v158, v173, v173
	v_add_f32_e32 v157, v157, v158
	v_add_f32_e32 v156, v156, v157
	v_add_f32_e32 v156, v209, v156
	ds_bpermute_b32 v157, v0, v156
	s_waitcnt lgkmcnt(0)
	v_add_f32_e32 v156, v156, v157
	ds_bpermute_b32 v157, v208, v156
	s_and_saveexec_b64 s[72:73], s[40:41]
	s_cbranch_execz .LBB7_447
	v_lshlrev_b64 v[158:159], 6, v[198:199]
	v_lshl_add_u64 v[158:159], s[66:67], 0, v[158:159]
	v_lshl_add_u64 v[158:159], s[16:17], 2, v[158:159]
	s_lshl_b32 s20, s96, 2
	v_lshl_add_u64 v[158:159], v[158:159], 0, s[20:21]
	s_waitcnt lgkmcnt(0)
	v_add_f32_e32 v156, v156, v157
	global_store_dword v[158:159], v156, off

.LBB7_1107:
	s_waitcnt lgkmcnt(0)
	v_lshl_or_b32 v2, s57, 8, v206
	v_lshl_add_u32 v184, s88, 8, v204
	v_ashrrev_i32_e32 v3, 31, v2
	v_lshlrev_b64 v[132:133], 1, v[2:3]
	v_ashrrev_i32_e32 v185, 31, v184
	v_lshl_add_u64 v[190:191], s[68:69], 0, v[132:133]
	v_lshlrev_b64 v[134:135], 11, v[184:185]
	v_lshl_add_u64 v[136:137], v[190:191], 0, v[134:135]
	global_load_dwordx4 v[196:199], v[136:137], off
	global_load_dwordx4 v[208:211], v[136:137], off offset:256
	v_or_b32_e32 v192, 16, v184
	v_or_b32_e32 v186, 32, v184
	v_or_b32_e32 v156, 48, v184
	v_ashrrev_i32_e32 v193, 31, v192
	v_ashrrev_i32_e32 v187, 31, v186
	v_ashrrev_i32_e32 v157, 31, v156
	v_lshlrev_b64 v[194:195], 11, v[192:193]
	v_lshlrev_b64 v[188:189], 11, v[186:187]
	v_lshlrev_b64 v[158:159], 11, v[156:157]
	v_lshl_add_u64 v[134:135], s[68:69], 0, v[134:135]
	v_lshl_add_u64 v[136:137], v[190:191], 0, v[194:195]
	v_lshl_add_u64 v[138:139], v[190:191], 0, v[188:189]
	v_lshl_add_u64 v[170:171], v[190:191], 0, v[158:159]
	v_lshl_add_u64 v[172:173], v[134:135], 0, v[132:133]
	global_load_dwordx4 v[152:155], v[136:137], off
	global_load_dwordx4 v[148:151], v[136:137], off offset:256
	global_load_dwordx4 v[144:147], v[138:139], off
	global_load_dwordx4 v[140:143], v[138:139], off offset:256
	s_nop 0
	global_load_dwordx4 v[136:139], v[170:171], off
	global_load_dwordx4 v[132:135], v[170:171], off offset:256
	v_add_u32_e32 v248, 0x80, v184
	v_ashrrev_i32_e32 v249, 31, v248
	v_lshlrev_b64 v[248:249], 11, v[248:249]
	v_lshl_add_u64 v[248:249], v[190:191], 0, v[248:249]
	global_load_dwordx4 v[232:235], v[248:249], off
	global_load_dwordx4 v[236:239], v[248:249], off offset:256
	s_mov_b64 s[72:73], 0x8000
	v_lshl_add_u64 v[248:249], v[248:249], 0, s[72:73]
	global_load_dwordx4 v[240:243], v[248:249], off
	global_load_dwordx4 v[244:247], v[248:249], off offset:256
	s_waitcnt vmcnt(0)
	v_lshlrev_b32_e32 v212, 16, v198
	v_and_b32_e32 v213, 0xffff0000, v198
	v_lshlrev_b32_e32 v198, 16, v199
	v_and_b32_e32 v199, 0xffff0000, v199
	v_lshlrev_b32_e32 v170, 16, v196
	v_and_b32_e32 v171, 0xffff0000, v196
	v_lshlrev_b32_e32 v196, 16, v197
	v_and_b32_e32 v197, 0xffff0000, v197
	v_pk_add_f32 v[220:221], v[126:127], v[198:199]
	v_pk_add_f32 v[198:199], v[124:125], v[212:213]
	v_lshlrev_b32_e32 v214, 16, v208
	v_and_b32_e32 v215, 0xffff0000, v208
	v_lshlrev_b32_e32 v208, 16, v209
	v_and_b32_e32 v209, 0xffff0000, v209
	v_lshlrev_b32_e32 v216, 16, v210
	v_and_b32_e32 v217, 0xffff0000, v210
	v_lshlrev_b32_e32 v210, 16, v211
	v_and_b32_e32 v211, 0xffff0000, v211
	v_pk_add_f32 v[218:219], v[130:131], v[196:197]
	v_pk_add_f32 v[170:171], v[128:129], v[170:171]
	v_pk_add_f32 v[208:209], v[98:99], v[208:209]
	v_cvt_pk_bf16_f32 v196, v170, v171
	v_cvt_pk_bf16_f32 v197, v218, v219
	v_cvt_pk_bf16_f32 v198, v198, v199
	v_cvt_pk_bf16_f32 v199, v220, v221
	v_pk_add_f32 v[212:213], v[96:97], v[214:215]
	v_pk_add_f32 v[214:215], v[94:95], v[210:211]
	global_store_dwordx4 v[172:173], v[196:199], off
	v_lshlrev_b32_e32 v0, 16, v196
	v_and_b32_e32 v170, 0xffff0000, v196
	v_lshlrev_b32_e32 v171, 16, v197
	v_and_b32_e32 v196, 0xffff0000, v197
	v_lshlrev_b32_e32 v197, 16, v198
	v_and_b32_e32 v198, 0xffff0000, v198
	v_lshlrev_b32_e32 v218, 16, v199
	v_and_b32_e32 v199, 0xffff0000, v199
	v_pk_add_f32 v[216:217], v[92:93], v[216:217]
	v_cvt_pk_bf16_f32 v210, v212, v213
	v_cvt_pk_bf16_f32 v211, v208, v209
	v_mul_f32_e32 v170, v170, v170
	v_cvt_pk_bf16_f32 v212, v216, v217
	v_cvt_pk_bf16_f32 v213, v214, v215
	v_mul_f32_e32 v196, v196, v196
	v_mul_f32_e32 v198, v198, v198
	v_mul_f32_e32 v199, v199, v199
	v_and_b32_e32 v209, 0xffff0000, v210
	v_and_b32_e32 v215, 0xffff0000, v211
	v_lshlrev_b32_e32 v208, 16, v210
	v_lshlrev_b32_e32 v214, 16, v211
	v_fmac_f32_e32 v170, v0, v0
	v_fmac_f32_e32 v196, v171, v171
	v_fmac_f32_e32 v198, v197, v197
	v_fmac_f32_e32 v199, v218, v218
	v_mul_f32_e32 v0, v209, v209
	v_mul_f32_e32 v171, v215, v215
	v_and_b32_e32 v217, 0xffff0000, v212
	v_and_b32_e32 v220, 0xffff0000, v213
	v_add_f32_e32 v170, v170, v196
	v_add_f32_e32 v196, v198, v199
	v_fmac_f32_e32 v0, v208, v208
	v_fmac_f32_e32 v171, v214, v214
	v_lshlrev_b32_e32 v216, 16, v212
	v_lshlrev_b32_e32 v219, 16, v213
	v_add_f32_e32 v170, v170, v196
	v_add_f32_e32 v0, v0, v171
	v_mul_f32_e32 v171, v217, v217
	v_mul_f32_e32 v196, v220, v220
	v_fmac_f32_e32 v171, v216, v216
	v_fmac_f32_e32 v196, v219, v219
	v_add_f32_e32 v171, v171, v196
	v_add_f32_e32 v0, v0, v171
	v_and_b32_e32 v171, 64, v163
	v_add_f32_e32 v170, v170, v0
	v_xor_b32_e32 v0, 16, v163
	v_add_u32_e32 v171, 64, v171
	v_cmp_lt_i32_e32 vcc, v0, v171
	global_store_dwordx4 v[172:173], v[210:213], off offset:256
	s_nop 0
	v_cndmask_b32_e32 v0, v163, v0, vcc
	v_lshlrev_b32_e32 v0, 2, v0
	ds_bpermute_b32 v196, v0, v170
	s_waitcnt lgkmcnt(0)
	v_add_f32_e32 v196, v170, v196
	v_xor_b32_e32 v170, 32, v163
	v_cmp_lt_i32_e32 vcc, v170, v171
	s_nop 1
	v_cndmask_b32_e32 v170, v163, v170, vcc
	v_lshlrev_b32_e32 v208, 2, v170
	ds_bpermute_b32 v197, v208, v196
	s_lshl_b32 vcc_lo, s57, 2
	s_ashr_i32 vcc_hi, vcc_lo, 31
	s_and_saveexec_b64 s[72:73], s[40:41]
	s_cbranch_execz .LBB7_1109
	v_lshlrev_b64 v[170:171], 6, v[184:185]
	v_lshl_add_u64 v[170:171], s[66:67], 0, v[170:171]
	v_lshl_add_u64 v[170:171], vcc, 2, v[170:171]
	s_lshl_b32 s20, s92, 2
	v_lshl_add_u64 v[170:171], v[170:171], 0, s[20:21]
	s_waitcnt lgkmcnt(0)
	v_add_f32_e32 v172, v196, v197
	global_store_dword v[170:171], v172, off

.LBB7_1115:
	s_or_b64 exec, exec, s[72:73]
	v_add_u32_e32 v198, 0x80, v184
	v_ashrrev_i32_e32 v199, 31, v198
	v_lshlrev_b64 v[170:171], 11, v[198:199]
	s_waitcnt lgkmcnt(0)
	v_lshl_add_u64 v[132:133], v[190:191], 0, v[170:171]
	v_mov_b64_e32 v[210:211], v[232:233]
	v_mov_b64_e32 v[212:213], v[234:235]
	v_mov_b64_e32 v[156:157], v[236:237]
	v_mov_b64_e32 v[158:159], v[238:239]
	v_add_u32_e32 v194, 0x90, v184
	v_ashrrev_i32_e32 v195, 31, v194
	v_add_u32_e32 v188, 0xa0, v184
	v_lshlrev_b64 v[196:197], 11, v[194:195]
	v_ashrrev_i32_e32 v189, 31, v188
	v_add_u32_e32 v184, 0xb0, v184
	v_lshl_add_u64 v[132:133], v[190:191], 0, v[196:197]
	v_lshlrev_b64 v[192:193], 11, v[188:189]
	v_ashrrev_i32_e32 v185, 31, v184
	v_mov_b64_e32 v[152:153], v[240:241]
	v_mov_b64_e32 v[154:155], v[242:243]
	v_mov_b64_e32 v[148:149], v[244:245]
	v_mov_b64_e32 v[150:151], v[246:247]
	v_lshl_add_u64 v[132:133], v[190:191], 0, v[192:193]
	v_lshlrev_b64 v[186:187], 11, v[184:185]
	global_load_dwordx4 v[144:147], v[132:133], off
	global_load_dwordx4 v[140:143], v[132:133], off offset:256
	v_lshl_add_u64 v[132:133], v[190:191], 0, v[186:187]
	global_load_dwordx4 v[136:139], v[132:133], off
	s_nop 0
	global_load_dwordx4 v[132:135], v[132:133], off offset:256
	v_lshl_add_u64 v[170:171], s[68:69], 0, v[170:171]
	v_lshl_add_u64 v[170:171], v[2:3], 1, v[170:171]
	s_waitcnt vmcnt(7)
	v_lshlrev_b32_e32 v172, 16, v210
	v_and_b32_e32 v173, 0xffff0000, v210
	v_lshlrev_b32_e32 v190, 16, v211
	v_and_b32_e32 v191, 0xffff0000, v211
	v_lshlrev_b32_e32 v210, 16, v212
	v_and_b32_e32 v211, 0xffff0000, v212
	v_lshlrev_b32_e32 v212, 16, v213
	v_and_b32_e32 v213, 0xffff0000, v213
	v_pk_add_f32 v[172:173], v[64:65], v[172:173]
	v_pk_add_f32 v[190:191], v[66:67], v[190:191]
	v_pk_add_f32 v[214:215], v[62:63], v[212:213]
	v_pk_add_f32 v[212:213], v[60:61], v[210:211]
	v_cvt_pk_bf16_f32 v210, v172, v173
	v_cvt_pk_bf16_f32 v211, v190, v191
	s_nop 0
	v_and_b32_e32 v173, 0xffff0000, v210
	v_lshlrev_b32_e32 v172, 16, v210
	v_and_b32_e32 v191, 0xffff0000, v211
	v_mul_f32_e32 v173, v173, v173
	v_cvt_pk_bf16_f32 v212, v212, v213
	v_lshlrev_b32_e32 v190, 16, v211
	v_fmac_f32_e32 v173, v172, v172
	v_mul_f32_e32 v172, v191, v191
	v_cvt_pk_bf16_f32 v213, v214, v215
	global_store_dwordx4 v[170:171], v[210:213], off
	v_lshlrev_b32_e32 v209, 16, v212
	v_fmac_f32_e32 v172, v190, v190
	v_and_b32_e32 v210, 0xffff0000, v212
	v_and_b32_e32 v212, 0xffff0000, v213
	v_lshlrev_b32_e32 v211, 16, v213
	v_add_f32_e32 v172, v173, v172
	v_mul_f32_e32 v173, v210, v210
	v_mul_f32_e32 v190, v212, v212
	v_fmac_f32_e32 v173, v209, v209
	v_fmac_f32_e32 v190, v211, v211
	v_add_f32_e32 v173, v173, v190
	v_add_f32_e32 v209, v172, v173
	s_waitcnt vmcnt(7)
	v_lshlrev_b32_e32 v172, 16, v156
	v_and_b32_e32 v173, 0xffff0000, v156
	v_lshlrev_b32_e32 v156, 16, v157
	v_and_b32_e32 v157, 0xffff0000, v157
	v_lshlrev_b32_e32 v190, 16, v158
	v_and_b32_e32 v191, 0xffff0000, v158
	v_lshlrev_b32_e32 v158, 16, v159
	v_and_b32_e32 v159, 0xffff0000, v159
	v_pk_add_f32 v[210:211], v[34:35], v[156:157]
	v_pk_add_f32 v[156:157], v[32:33], v[172:173]
	v_pk_add_f32 v[172:173], v[30:31], v[158:159]
	v_pk_add_f32 v[158:159], v[28:29], v[190:191]
	v_cvt_pk_bf16_f32 v156, v156, v157
	v_cvt_pk_bf16_f32 v157, v210, v211
	s_nop 0
	v_cvt_pk_bf16_f32 v158, v158, v159
	v_cvt_pk_bf16_f32 v159, v172, v173
	global_store_dwordx4 v[170:171], v[156:159], off offset:256
	v_lshlrev_b32_e32 v170, 16, v156
	v_lshlrev_b32_e32 v171, 16, v157
	v_and_b32_e32 v156, 0xffff0000, v156
	v_and_b32_e32 v157, 0xffff0000, v157
	v_mul_f32_e32 v156, v156, v156
	v_mul_f32_e32 v157, v157, v157
	v_lshlrev_b32_e32 v172, 16, v158
	v_and_b32_e32 v158, 0xffff0000, v158
	v_lshlrev_b32_e32 v173, 16, v159
	v_and_b32_e32 v159, 0xffff0000, v159
	v_fmac_f32_e32 v156, v170, v170
	v_fmac_f32_e32 v157, v171, v171
	v_add_f32_e32 v156, v156, v157
	v_mul_f32_e32 v157, v158, v158
	v_mul_f32_e32 v158, v159, v159
	v_fmac_f32_e32 v157, v172, v172
	v_fmac_f32_e32 v158, v173, v173
	v_add_f32_e32 v157, v157, v158
	v_add_f32_e32 v156, v156, v157
	v_add_f32_e32 v156, v209, v156
	ds_bpermute_b32 v157, v0, v156
	s_waitcnt lgkmcnt(0)
	v_add_f32_e32 v156, v156, v157
	ds_bpermute_b32 v157, v208, v156
	s_and_saveexec_b64 s[72:73], s[40:41]
	s_cbranch_execz .LBB7_1117
	v_lshlrev_b64 v[158:159], 6, v[198:199]
	v_lshl_add_u64 v[158:159], s[66:67], 0, v[158:159]
	v_lshl_add_u64 v[158:159], vcc, 2, v[158:159]
	s_lshl_b32 s20, s92, 2
	v_lshl_add_u64 v[158:159], v[158:159], 0, s[20:21]
	s_waitcnt lgkmcnt(0)
	v_add_f32_e32 v156, v156, v157
	global_store_dword v[158:159], v156, off
